# 64B-aligned heads for the six GEMM inner loops on top of v6 (P8 epilogue rewrite etc)
# speedup vs baseline: 1.0284x; 1.0069x over previous
; #define PG8_LDA(dst, b, h) do { _Pragma("unroll") for (int m = 0; m < 4; ++m) _Pragma("unroll") for (int k = 0; k < 2; ++k) dst[m][k] = *(const LAS bf16x8*)(lds + PG8_SA(b, h) + aoff + m * 2048 + k * 1024); } while (0)
; template <class Epi>
; __device__ __forceinline__ void gemm_phase(LAS unsigned char* lds, const Gemm g, const Order& S, const Epi& E) {
;     ...
;         const bool has_next = S.next(ui + 1, nxt);
;         const char* nA = has_next ? (const char*)g.A + nxt.aoff : cA; const char* nB = has_next ? (const char*)g.Bt + nxt.boff : cB;
;         for (int t = 0; t < nt; t += 2) {
;             const bool last = (t == nt - 2);
;             const char* a1 = cA + (size_t)(t + 1) * kstep;
;             const char* a2 = last ? nA : cA + (size_t)(t + 2) * kstep; const char* b2 = last ? nB : cB + (size_t)(t + 2) * kstep;
;             const char* a3 = a2 + kstep; const char* b3 = b2 + kstep;
;             PG8_LDB(B0, 0, 0); PG8_LDB(B1, 0, 1); PG8_SCHED; PG8_LDA(At, 0, 0); PG8_STAGE(PG8_SA(1, 1), a1 + hstepA, voffA);
;             PG8_WAIT_V(8); PG8_WAIT_L(0); PG8_BAR; PG8_MMA(0, 0, At, B0); PG8_MMA(0, 1, At, B1); PG8_BAR; PG8_SCHED;
;             PG8_LDA(At, 0, 1); PG8_STAGE(PG8_SB(0, 0), b2, voffB); PG8_STAGE(PG8_SB(0, 1), b2 + hstepB, voffB); PG8_STAGE(PG8_SA(0, 0), a2, voffA);
;             PG8_WAIT_V(8); PG8_WAIT_L(0); PG8_BAR; PG8_MMA(1, 0, At, B0); PG8_MMA(1, 1, At, B1); PG8_BAR; PG8_SCHED;
;             PG8_LDB(B0, 1, 0); PG8_LDB(B1, 1, 1); PG8_SCHED; PG8_LDA(At, 1, 0); PG8_STAGE(PG8_SA(0, 1), a2 + hstepA, voffA);
;             PG8_WAIT_V(8); PG8_WAIT_L(0); PG8_BAR; PG8_MMA(0, 0, At, B0); PG8_MMA(0, 1, At, B1); PG8_BAR; PG8_SCHED;
;             PG8_LDA(At, 1, 1); PG8_STAGE(PG8_SB(1, 0), b3, voffB); PG8_STAGE(PG8_SB(1, 1), b3 + hstepB, voffB); PG8_STAGE(PG8_SA(1, 0), a3, voffA);
;             PG8_WAIT_V(8); PG8_WAIT_L(0); PG8_BAR; PG8_MMA(1, 0, At, B0); PG8_MMA(1, 1, At, B1); PG8_BAR; PG8_SCHED;
;         }
;         if (wr == 0) PG8_BAR;
;         E(acc, cur, wr, wc, fr, fq);
;         if (!has_next) break;
; #pragma unroll
;         for (int a = 0; a < 2; ++a)
; #pragma unroll
;             for (int b = 0; b < 2; ++b)
; #pragma unroll
;                 for (int m = 0; m < 4; ++m)
; #pragma unroll
;                     for (int n = 0; n < 2; ++n) acc[a][b][m][n] = (f32x4){0.f, 0.f, 0.f, 0.f};
;         cur = nxt; cA = nA; cB = nB; ++ui;
.LBB0_135:
	s_add_u32 s38, s86, s34
	s_addc_u32 s39, s87, s35
	s_and_b64 s[12:13], s[4:5], exec
	s_cselect_b32 s1, s39, s9
	s_cselect_b32 s2, s38, s8
	s_add_u32 s40, s72, s36
	s_addc_u32 s41, s73, s37
	s_and_b64 s[12:13], s[4:5], exec
	s_cselect_b32 s7, s41, s11
	s_cselect_b32 s29, s40, s10
	s_add_u32 s8, s8, 0x80080
	s_addc_u32 s9, s9, 0
	s_add_u32 s31, s10, 0x100
	v_mov_b32_e32 v0, 0
	s_addc_u32 s33, s11, 0
	s_mov_b32 s52, -2
	v_mov_b32_e32 v1, v0
	v_mov_b32_e32 v2, v0
	v_mov_b32_e32 v3, v0
	v_mov_b32_e32 v4, v0
	v_mov_b32_e32 v5, v0
	v_mov_b32_e32 v6, v0
	v_mov_b32_e32 v7, v0
	v_mov_b32_e32 v8, v0
	v_mov_b32_e32 v9, v0
	v_mov_b32_e32 v10, v0
	v_mov_b32_e32 v11, v0
	v_mov_b32_e32 v12, v0
	v_mov_b32_e32 v13, v0
	v_mov_b32_e32 v14, v0
	v_mov_b32_e32 v15, v0
	v_mov_b32_e32 v16, v0
	v_mov_b32_e32 v17, v0
	v_mov_b32_e32 v18, v0
	v_mov_b32_e32 v19, v0
	v_mov_b32_e32 v20, v0
	v_mov_b32_e32 v21, v0
	v_mov_b32_e32 v22, v0
	v_mov_b32_e32 v23, v0
	v_mov_b32_e32 v24, v0
	v_mov_b32_e32 v25, v0
	v_mov_b32_e32 v26, v0
	v_mov_b32_e32 v27, v0
	v_mov_b32_e32 v28, v0
	v_mov_b32_e32 v29, v0
	v_mov_b32_e32 v30, v0
	v_mov_b32_e32 v31, v0
	v_mov_b32_e32 v64, v0
	v_mov_b32_e32 v65, v0
	v_mov_b32_e32 v66, v0
	v_mov_b32_e32 v67, v0
	v_mov_b32_e32 v68, v0
	v_mov_b32_e32 v69, v0
	v_mov_b32_e32 v70, v0
	v_mov_b32_e32 v71, v0
	v_mov_b32_e32 v72, v0
	v_mov_b32_e32 v73, v0
	v_mov_b32_e32 v74, v0
	v_mov_b32_e32 v75, v0
	v_mov_b32_e32 v76, v0
	v_mov_b32_e32 v77, v0
	v_mov_b32_e32 v78, v0
	v_mov_b32_e32 v79, v0
	v_mov_b32_e32 v80, v0
	v_mov_b32_e32 v81, v0
	v_mov_b32_e32 v82, v0
	v_mov_b32_e32 v83, v0
	v_mov_b32_e32 v84, v0
	v_mov_b32_e32 v85, v0
	v_mov_b32_e32 v86, v0
	v_mov_b32_e32 v87, v0
	v_mov_b32_e32 v88, v0
	v_mov_b32_e32 v89, v0
	v_mov_b32_e32 v90, v0
	v_mov_b32_e32 v91, v0
	v_mov_b32_e32 v92, v0
	v_mov_b32_e32 v93, v0
	v_mov_b32_e32 v94, v0
	v_mov_b32_e32 v95, v0
	v_mov_b32_e32 v32, v0
	v_mov_b32_e32 v33, v0
	v_mov_b32_e32 v34, v0
	v_mov_b32_e32 v35, v0
	v_mov_b32_e32 v36, v0
	v_mov_b32_e32 v37, v0
	v_mov_b32_e32 v38, v0
	v_mov_b32_e32 v39, v0
	v_mov_b32_e32 v40, v0
	v_mov_b32_e32 v41, v0
	v_mov_b32_e32 v42, v0
	v_mov_b32_e32 v43, v0
	v_mov_b32_e32 v44, v0
	v_mov_b32_e32 v45, v0
	v_mov_b32_e32 v46, v0
	v_mov_b32_e32 v47, v0
	v_mov_b32_e32 v48, v0
	v_mov_b32_e32 v49, v0
	v_mov_b32_e32 v50, v0
	v_mov_b32_e32 v51, v0
	v_mov_b32_e32 v52, v0
	v_mov_b32_e32 v53, v0
	v_mov_b32_e32 v54, v0
	v_mov_b32_e32 v55, v0
	v_mov_b32_e32 v56, v0
	v_mov_b32_e32 v57, v0
	v_mov_b32_e32 v58, v0
	v_mov_b32_e32 v59, v0
	v_mov_b32_e32 v60, v0
	v_mov_b32_e32 v61, v0
	v_mov_b32_e32 v62, v0
	v_mov_b32_e32 v63, v0
	v_mov_b32_e32 v96, v0
	v_mov_b32_e32 v97, v0
	v_mov_b32_e32 v98, v0
	v_mov_b32_e32 v99, v0
	v_mov_b32_e32 v100, v0
	v_mov_b32_e32 v101, v0
	v_mov_b32_e32 v102, v0
	v_mov_b32_e32 v103, v0
	v_mov_b32_e32 v104, v0
	v_mov_b32_e32 v105, v0
	v_mov_b32_e32 v106, v0
	v_mov_b32_e32 v107, v0
	v_mov_b32_e32 v108, v0
	v_mov_b32_e32 v109, v0
	v_mov_b32_e32 v110, v0
	v_mov_b32_e32 v111, v0
	v_mov_b32_e32 v112, v0
	v_mov_b32_e32 v113, v0
	v_mov_b32_e32 v114, v0
	v_mov_b32_e32 v115, v0
	v_mov_b32_e32 v116, v0
	v_mov_b32_e32 v117, v0
	v_mov_b32_e32 v118, v0
	v_mov_b32_e32 v119, v0
	v_mov_b32_e32 v120, v0
	v_mov_b32_e32 v121, v0
	v_mov_b32_e32 v122, v0
	v_mov_b32_e32 v123, v0
	v_mov_b32_e32 v124, v0
	v_mov_b32_e32 v125, v0
	v_mov_b32_e32 v126, v0
	v_mov_b32_e32 v127, v0
	.p2align 6

; #define PG8_LDA(dst, b, h) do { _Pragma("unroll") for (int m = 0; m < 4; ++m) _Pragma("unroll") for (int k = 0; k < 2; ++k) dst[m][k] = *(const LAS bf16x8*)(lds + PG8_SA(b, h) + aoff + m * 2048 + k * 1024); } while (0)
; template <class Epi>
; __device__ __forceinline__ void gemm_phase(LAS unsigned char* lds, const Gemm g, const Order& S, const Epi& E) {
;     ...
;         const bool has_next = S.next(ui + 1, nxt);
;         const char* nA = has_next ? (const char*)g.A + nxt.aoff : cA; const char* nB = has_next ? (const char*)g.Bt + nxt.boff : cB;
;         for (int t = 0; t < nt; t += 2) {
;             const bool last = (t == nt - 2);
;             const char* a1 = cA + (size_t)(t + 1) * kstep;
;             const char* a2 = last ? nA : cA + (size_t)(t + 2) * kstep; const char* b2 = last ? nB : cB + (size_t)(t + 2) * kstep;
;             const char* a3 = a2 + kstep; const char* b3 = b2 + kstep;
;             PG8_LDB(B0, 0, 0); PG8_LDB(B1, 0, 1); PG8_SCHED; PG8_LDA(At, 0, 0); PG8_STAGE(PG8_SA(1, 1), a1 + hstepA, voffA);
;             PG8_WAIT_V(8); PG8_WAIT_L(0); PG8_BAR; PG8_MMA(0, 0, At, B0); PG8_MMA(0, 1, At, B1); PG8_BAR; PG8_SCHED;
;             PG8_LDA(At, 0, 1); PG8_STAGE(PG8_SB(0, 0), b2, voffB); PG8_STAGE(PG8_SB(0, 1), b2 + hstepB, voffB); PG8_STAGE(PG8_SA(0, 0), a2, voffA);
;             PG8_WAIT_V(8); PG8_WAIT_L(0); PG8_BAR; PG8_MMA(1, 0, At, B0); PG8_MMA(1, 1, At, B1); PG8_BAR; PG8_SCHED;
;             PG8_LDB(B0, 1, 0); PG8_LDB(B1, 1, 1); PG8_SCHED; PG8_LDA(At, 1, 0); PG8_STAGE(PG8_SA(0, 1), a2 + hstepA, voffA);
;             PG8_WAIT_V(8); PG8_WAIT_L(0); PG8_BAR; PG8_MMA(0, 0, At, B0); PG8_MMA(0, 1, At, B1); PG8_BAR; PG8_SCHED;
;             PG8_LDA(At, 1, 1); PG8_STAGE(PG8_SB(1, 0), b3, voffB); PG8_STAGE(PG8_SB(1, 1), b3 + hstepB, voffB); PG8_STAGE(PG8_SA(1, 0), a3, voffA);
;             PG8_WAIT_V(8); PG8_WAIT_L(0); PG8_BAR; PG8_MMA(1, 0, At, B0); PG8_MMA(1, 1, At, B1); PG8_BAR; PG8_SCHED;
;         }
;         if (wr == 0) PG8_BAR;
;         E(acc, cur, wr, wc, fr, fq);
;         if (!has_next) break;
; #pragma unroll
;         for (int a = 0; a < 2; ++a)
; #pragma unroll
;             for (int b = 0; b < 2; ++b)
; #pragma unroll
;                 for (int m = 0; m < 4; ++m)
; #pragma unroll
;                     for (int n = 0; n < 2; ++n) acc[a][b][m][n] = (f32x4){0.f, 0.f, 0.f, 0.f};
;         cur = nxt; cA = nA; cB = nB; ++ui;
.LBB0_538:
	s_add_u32 s24, s86, s20
	s_addc_u32 s25, s87, s21
	s_and_b64 s[26:27], s[6:7], exec
	s_cselect_b32 s17, s25, s31
	s_cselect_b32 s19, s24, s30
	s_add_u32 s26, s2, s22
	s_addc_u32 s27, s3, s23
	s_and_b64 s[36:37], s[6:7], exec
	s_cselect_b32 s29, s27, s35
	s_cselect_b32 s52, s26, s34
	s_add_u32 s30, s30, 0x80080
	s_addc_u32 s31, s31, 0
	s_add_u32 s53, s34, 0x100
	v_mov_b32_e32 v0, 0
	s_addc_u32 s54, s35, 0
	s_mov_b32 s55, -2
	s_waitcnt lgkmcnt(0)
	v_mov_b32_e32 v1, v0
	v_mov_b32_e32 v2, v0
	v_mov_b32_e32 v3, v0
	v_mov_b32_e32 v4, v0
	v_mov_b32_e32 v5, v0
	v_mov_b32_e32 v6, v0
	v_mov_b32_e32 v7, v0
	v_mov_b32_e32 v16, v0
	v_mov_b32_e32 v17, v0
	v_mov_b32_e32 v18, v0
	v_mov_b32_e32 v19, v0
	v_mov_b32_e32 v20, v0
	v_mov_b32_e32 v21, v0
	v_mov_b32_e32 v22, v0
	v_mov_b32_e32 v23, v0
	v_mov_b32_e32 v32, v0
	v_mov_b32_e32 v33, v0
	v_mov_b32_e32 v34, v0
	v_mov_b32_e32 v35, v0
	v_mov_b32_e32 v36, v0
	v_mov_b32_e32 v37, v0
	v_mov_b32_e32 v38, v0
	v_mov_b32_e32 v39, v0
	v_mov_b32_e32 v48, v0
	v_mov_b32_e32 v49, v0
	v_mov_b32_e32 v50, v0
	v_mov_b32_e32 v51, v0
	v_mov_b32_e32 v52, v0
	v_mov_b32_e32 v53, v0
	v_mov_b32_e32 v54, v0
	v_mov_b32_e32 v55, v0
	v_mov_b32_e32 v8, v0
	v_mov_b32_e32 v9, v0
	v_mov_b32_e32 v10, v0
	v_mov_b32_e32 v11, v0
	v_mov_b32_e32 v12, v0
	v_mov_b32_e32 v13, v0
	v_mov_b32_e32 v14, v0
	v_mov_b32_e32 v15, v0
	v_mov_b32_e32 v24, v0
	v_mov_b32_e32 v25, v0
	v_mov_b32_e32 v26, v0
	v_mov_b32_e32 v27, v0
	v_mov_b32_e32 v28, v0
	v_mov_b32_e32 v29, v0
	v_mov_b32_e32 v30, v0
	v_mov_b32_e32 v31, v0
	v_mov_b32_e32 v40, v0
	v_mov_b32_e32 v41, v0
	v_mov_b32_e32 v42, v0
	v_mov_b32_e32 v43, v0
	v_mov_b32_e32 v44, v0
	v_mov_b32_e32 v45, v0
	v_mov_b32_e32 v46, v0
	v_mov_b32_e32 v47, v0
	v_mov_b32_e32 v56, v0
	v_mov_b32_e32 v57, v0
	v_mov_b32_e32 v58, v0
	v_mov_b32_e32 v59, v0
	v_mov_b32_e32 v60, v0
	v_mov_b32_e32 v61, v0
	v_mov_b32_e32 v62, v0
	v_mov_b32_e32 v63, v0
	v_mov_b32_e32 v64, v0
	v_mov_b32_e32 v65, v0
	v_mov_b32_e32 v66, v0
	v_mov_b32_e32 v67, v0
	v_mov_b32_e32 v68, v0
	v_mov_b32_e32 v69, v0
	v_mov_b32_e32 v70, v0
	v_mov_b32_e32 v71, v0
	v_mov_b32_e32 v80, v0
	v_mov_b32_e32 v81, v0
	v_mov_b32_e32 v82, v0
	v_mov_b32_e32 v83, v0
	v_mov_b32_e32 v84, v0
	v_mov_b32_e32 v85, v0
	v_mov_b32_e32 v86, v0
	v_mov_b32_e32 v87, v0
	v_mov_b32_e32 v96, v0
	v_mov_b32_e32 v97, v0
	v_mov_b32_e32 v98, v0
	v_mov_b32_e32 v99, v0
	v_mov_b32_e32 v100, v0
	v_mov_b32_e32 v101, v0
	v_mov_b32_e32 v102, v0
	v_mov_b32_e32 v103, v0
	v_mov_b32_e32 v112, v0
	v_mov_b32_e32 v113, v0
	v_mov_b32_e32 v114, v0
	v_mov_b32_e32 v115, v0
	v_mov_b32_e32 v116, v0
	v_mov_b32_e32 v117, v0
	v_mov_b32_e32 v118, v0
	v_mov_b32_e32 v119, v0
	v_mov_b32_e32 v72, v0
	v_mov_b32_e32 v73, v0
	v_mov_b32_e32 v74, v0
	v_mov_b32_e32 v75, v0
	v_mov_b32_e32 v76, v0
	v_mov_b32_e32 v77, v0
	v_mov_b32_e32 v78, v0
	v_mov_b32_e32 v79, v0
	v_mov_b32_e32 v88, v0
	v_mov_b32_e32 v89, v0
	v_mov_b32_e32 v90, v0
	v_mov_b32_e32 v91, v0
	v_mov_b32_e32 v92, v0
	v_mov_b32_e32 v93, v0
	v_mov_b32_e32 v94, v0
	v_mov_b32_e32 v95, v0
	v_mov_b32_e32 v104, v0
	v_mov_b32_e32 v105, v0
	v_mov_b32_e32 v106, v0
	v_mov_b32_e32 v107, v0
	v_mov_b32_e32 v108, v0
	v_mov_b32_e32 v109, v0
	v_mov_b32_e32 v110, v0
	v_mov_b32_e32 v111, v0
	v_mov_b32_e32 v120, v0
	v_mov_b32_e32 v121, v0
	v_mov_b32_e32 v122, v0
	v_mov_b32_e32 v123, v0
	v_mov_b32_e32 v124, v0
	v_mov_b32_e32 v125, v0
	v_mov_b32_e32 v126, v0
	v_mov_b32_e32 v127, v0
	.p2align 6

; #define PG8_LDA(dst, b, h) do { _Pragma("unroll") for (int m = 0; m < 4; ++m) _Pragma("unroll") for (int k = 0; k < 2; ++k) dst[m][k] = *(const LAS bf16x8*)(lds + PG8_SA(b, h) + aoff + m * 2048 + k * 1024); } while (0)
; template <class Epi>
; __device__ __forceinline__ void gemm_phase(LAS unsigned char* lds, const Gemm g, const Order& S, const Epi& E) {
;     ...
;         const bool has_next = S.next(ui + 1, nxt);
;         const char* nA = has_next ? (const char*)g.A + nxt.aoff : cA; const char* nB = has_next ? (const char*)g.Bt + nxt.boff : cB;
;         for (int t = 0; t < nt; t += 2) {
;             const bool last = (t == nt - 2);
;             const char* a1 = cA + (size_t)(t + 1) * kstep;
;             const char* a2 = last ? nA : cA + (size_t)(t + 2) * kstep; const char* b2 = last ? nB : cB + (size_t)(t + 2) * kstep;
;             const char* a3 = a2 + kstep; const char* b3 = b2 + kstep;
;             PG8_LDB(B0, 0, 0); PG8_LDB(B1, 0, 1); PG8_SCHED; PG8_LDA(At, 0, 0); PG8_STAGE(PG8_SA(1, 1), a1 + hstepA, voffA);
;             PG8_WAIT_V(8); PG8_WAIT_L(0); PG8_BAR; PG8_MMA(0, 0, At, B0); PG8_MMA(0, 1, At, B1); PG8_BAR; PG8_SCHED;
;             PG8_LDA(At, 0, 1); PG8_STAGE(PG8_SB(0, 0), b2, voffB); PG8_STAGE(PG8_SB(0, 1), b2 + hstepB, voffB); PG8_STAGE(PG8_SA(0, 0), a2, voffA);
;             PG8_WAIT_V(8); PG8_WAIT_L(0); PG8_BAR; PG8_MMA(1, 0, At, B0); PG8_MMA(1, 1, At, B1); PG8_BAR; PG8_SCHED;
;             PG8_LDB(B0, 1, 0); PG8_LDB(B1, 1, 1); PG8_SCHED; PG8_LDA(At, 1, 0); PG8_STAGE(PG8_SA(0, 1), a2 + hstepA, voffA);
;             PG8_WAIT_V(8); PG8_WAIT_L(0); PG8_BAR; PG8_MMA(0, 0, At, B0); PG8_MMA(0, 1, At, B1); PG8_BAR; PG8_SCHED;
;             PG8_LDA(At, 1, 1); PG8_STAGE(PG8_SB(1, 0), b3, voffB); PG8_STAGE(PG8_SB(1, 1), b3 + hstepB, voffB); PG8_STAGE(PG8_SA(1, 0), a3, voffA);
;             PG8_WAIT_V(8); PG8_WAIT_L(0); PG8_BAR; PG8_MMA(1, 0, At, B0); PG8_MMA(1, 1, At, B1); PG8_BAR; PG8_SCHED;
;         }
;         if (wr == 0) PG8_BAR;
;         E(acc, cur, wr, wc, fr, fq);
;         if (!has_next) break;
; #pragma unroll
;         for (int a = 0; a < 2; ++a)
; #pragma unroll
;             for (int b = 0; b < 2; ++b)
; #pragma unroll
;                 for (int m = 0; m < 4; ++m)
; #pragma unroll
;                     for (int n = 0; n < 2; ++n) acc[a][b][m][n] = (f32x4){0.f, 0.f, 0.f, 0.f};
;         cur = nxt; cA = nA; cB = nB; ++ui;
.LBB0_660:
	s_add_u32 s34, s44, s28
	s_addc_u32 s35, s45, s29
	s_and_b64 s[0:1], s[6:7], exec
	s_cselect_b32 s0, s35, s41
	s_cselect_b32 s1, s34, s40
	s_add_u32 s36, s49, s30
	s_addc_u32 s37, s50, s31
	s_and_b64 s[46:47], s[6:7], exec
	s_cselect_b32 s2, s37, s43
	s_cselect_b32 s27, s36, s42
	s_add_u32 s40, s40, 0x80080
	s_addc_u32 s41, s41, 0
	s_add_u32 s33, s42, 0x100
	v_mov_b32_e32 v0, 0
	s_addc_u32 s39, s43, 0
	s_mov_b32 s81, -2
	v_mov_b32_e32 v1, v0
	v_mov_b32_e32 v2, v0
	v_mov_b32_e32 v3, v0
	v_mov_b32_e32 v4, v0
	v_mov_b32_e32 v5, v0
	v_mov_b32_e32 v6, v0
	v_mov_b32_e32 v7, v0
	v_mov_b32_e32 v16, v0
	v_mov_b32_e32 v17, v0
	v_mov_b32_e32 v18, v0
	v_mov_b32_e32 v19, v0
	v_mov_b32_e32 v20, v0
	v_mov_b32_e32 v21, v0
	v_mov_b32_e32 v22, v0
	v_mov_b32_e32 v23, v0
	v_mov_b32_e32 v32, v0
	v_mov_b32_e32 v33, v0
	v_mov_b32_e32 v34, v0
	v_mov_b32_e32 v35, v0
	v_mov_b32_e32 v36, v0
	v_mov_b32_e32 v37, v0
	v_mov_b32_e32 v38, v0
	v_mov_b32_e32 v39, v0
	v_mov_b32_e32 v48, v0
	v_mov_b32_e32 v49, v0
	v_mov_b32_e32 v50, v0
	v_mov_b32_e32 v51, v0
	v_mov_b32_e32 v52, v0
	v_mov_b32_e32 v53, v0
	v_mov_b32_e32 v54, v0
	v_mov_b32_e32 v55, v0
	v_mov_b32_e32 v8, v0
	v_mov_b32_e32 v9, v0
	v_mov_b32_e32 v10, v0
	v_mov_b32_e32 v11, v0
	v_mov_b32_e32 v12, v0
	v_mov_b32_e32 v13, v0
	v_mov_b32_e32 v14, v0
	v_mov_b32_e32 v15, v0
	v_mov_b32_e32 v24, v0
	v_mov_b32_e32 v25, v0
	v_mov_b32_e32 v26, v0
	v_mov_b32_e32 v27, v0
	v_mov_b32_e32 v28, v0
	v_mov_b32_e32 v29, v0
	v_mov_b32_e32 v30, v0
	v_mov_b32_e32 v31, v0
	v_mov_b32_e32 v40, v0
	v_mov_b32_e32 v41, v0
	v_mov_b32_e32 v42, v0
	v_mov_b32_e32 v43, v0
	v_mov_b32_e32 v44, v0
	v_mov_b32_e32 v45, v0
	v_mov_b32_e32 v46, v0
	v_mov_b32_e32 v47, v0
	v_mov_b32_e32 v56, v0
	v_mov_b32_e32 v57, v0
	v_mov_b32_e32 v58, v0
	v_mov_b32_e32 v59, v0
	v_mov_b32_e32 v60, v0
	v_mov_b32_e32 v61, v0
	v_mov_b32_e32 v62, v0
	v_mov_b32_e32 v63, v0
	v_mov_b32_e32 v64, v0
	v_mov_b32_e32 v65, v0
	v_mov_b32_e32 v66, v0
	v_mov_b32_e32 v67, v0
	v_mov_b32_e32 v68, v0
	v_mov_b32_e32 v69, v0
	v_mov_b32_e32 v70, v0
	v_mov_b32_e32 v71, v0
	v_mov_b32_e32 v80, v0
	v_mov_b32_e32 v81, v0
	v_mov_b32_e32 v82, v0
	v_mov_b32_e32 v83, v0
	v_mov_b32_e32 v84, v0
	v_mov_b32_e32 v85, v0
	v_mov_b32_e32 v86, v0
	v_mov_b32_e32 v87, v0
	v_mov_b32_e32 v96, v0
	v_mov_b32_e32 v97, v0
	v_mov_b32_e32 v98, v0
	v_mov_b32_e32 v99, v0
	v_mov_b32_e32 v100, v0
	v_mov_b32_e32 v101, v0
	v_mov_b32_e32 v102, v0
	v_mov_b32_e32 v103, v0
	v_mov_b32_e32 v112, v0
	v_mov_b32_e32 v113, v0
	v_mov_b32_e32 v114, v0
	v_mov_b32_e32 v115, v0
	v_mov_b32_e32 v116, v0
	v_mov_b32_e32 v117, v0
	v_mov_b32_e32 v118, v0
	v_mov_b32_e32 v119, v0
	v_mov_b32_e32 v72, v0
	v_mov_b32_e32 v73, v0
	v_mov_b32_e32 v74, v0
	v_mov_b32_e32 v75, v0
	v_mov_b32_e32 v76, v0
	v_mov_b32_e32 v77, v0
	v_mov_b32_e32 v78, v0
	v_mov_b32_e32 v79, v0
	v_mov_b32_e32 v88, v0
	v_mov_b32_e32 v89, v0
	v_mov_b32_e32 v90, v0
	v_mov_b32_e32 v91, v0
	v_mov_b32_e32 v92, v0
	v_mov_b32_e32 v93, v0
	v_mov_b32_e32 v94, v0
	v_mov_b32_e32 v95, v0
	v_mov_b32_e32 v104, v0
	v_mov_b32_e32 v105, v0
	v_mov_b32_e32 v106, v0
	v_mov_b32_e32 v107, v0
	v_mov_b32_e32 v108, v0
	v_mov_b32_e32 v109, v0
	v_mov_b32_e32 v110, v0
	v_mov_b32_e32 v111, v0
	v_mov_b32_e32 v120, v0
	v_mov_b32_e32 v121, v0
	v_mov_b32_e32 v122, v0
	v_mov_b32_e32 v123, v0
	v_mov_b32_e32 v124, v0
	v_mov_b32_e32 v125, v0
	v_mov_b32_e32 v126, v0
	v_mov_b32_e32 v127, v0
	.p2align 6

; #define PG8_LDA(dst, b, h) do { _Pragma("unroll") for (int m = 0; m < 4; ++m) _Pragma("unroll") for (int k = 0; k < 2; ++k) dst[m][k] = *(const LAS bf16x8*)(lds + PG8_SA(b, h) + aoff + m * 2048 + k * 1024); } while (0)
; template <class Epi>
; __device__ __forceinline__ void gemm_phase(LAS unsigned char* lds, const Gemm g, const Order& S, const Epi& E) {
;     ...
;         const bool has_next = S.next(ui + 1, nxt);
;         const char* nA = has_next ? (const char*)g.A + nxt.aoff : cA; const char* nB = has_next ? (const char*)g.Bt + nxt.boff : cB;
;         for (int t = 0; t < nt; t += 2) {
;             const bool last = (t == nt - 2);
;             const char* a1 = cA + (size_t)(t + 1) * kstep;
;             const char* a2 = last ? nA : cA + (size_t)(t + 2) * kstep; const char* b2 = last ? nB : cB + (size_t)(t + 2) * kstep;
;             const char* a3 = a2 + kstep; const char* b3 = b2 + kstep;
;             PG8_LDB(B0, 0, 0); PG8_LDB(B1, 0, 1); PG8_SCHED; PG8_LDA(At, 0, 0); PG8_STAGE(PG8_SA(1, 1), a1 + hstepA, voffA);
;             PG8_WAIT_V(8); PG8_WAIT_L(0); PG8_BAR; PG8_MMA(0, 0, At, B0); PG8_MMA(0, 1, At, B1); PG8_BAR; PG8_SCHED;
;             PG8_LDA(At, 0, 1); PG8_STAGE(PG8_SB(0, 0), b2, voffB); PG8_STAGE(PG8_SB(0, 1), b2 + hstepB, voffB); PG8_STAGE(PG8_SA(0, 0), a2, voffA);
;             PG8_WAIT_V(8); PG8_WAIT_L(0); PG8_BAR; PG8_MMA(1, 0, At, B0); PG8_MMA(1, 1, At, B1); PG8_BAR; PG8_SCHED;
;             PG8_LDB(B0, 1, 0); PG8_LDB(B1, 1, 1); PG8_SCHED; PG8_LDA(At, 1, 0); PG8_STAGE(PG8_SA(0, 1), a2 + hstepA, voffA);
;             PG8_WAIT_V(8); PG8_WAIT_L(0); PG8_BAR; PG8_MMA(0, 0, At, B0); PG8_MMA(0, 1, At, B1); PG8_BAR; PG8_SCHED;
;             PG8_LDA(At, 1, 1); PG8_STAGE(PG8_SB(1, 0), b3, voffB); PG8_STAGE(PG8_SB(1, 1), b3 + hstepB, voffB); PG8_STAGE(PG8_SA(1, 0), a3, voffA);
;             PG8_WAIT_V(8); PG8_WAIT_L(0); PG8_BAR; PG8_MMA(1, 0, At, B0); PG8_MMA(1, 1, At, B1); PG8_BAR; PG8_SCHED;
;         }
;         if (wr == 0) PG8_BAR;
;         E(acc, cur, wr, wc, fr, fq);
;         if (!has_next) break;
; #pragma unroll
;         for (int a = 0; a < 2; ++a)
; #pragma unroll
;             for (int b = 0; b < 2; ++b)
; #pragma unroll
;                 for (int m = 0; m < 4; ++m)
; #pragma unroll
;                     for (int n = 0; n < 2; ++n) acc[a][b][m][n] = (f32x4){0.f, 0.f, 0.f, 0.f};
;         cur = nxt; cA = nA; cB = nB; ++ui;
.LBB0_773:
	s_add_u32 s26, s20, s18
	s_addc_u32 s27, s21, s19
	s_and_b64 s[28:29], s[6:7], exec
	s_cselect_b32 s17, s27, s35
	s_cselect_b32 s31, s26, s34
	s_add_u32 s28, s2, s24
	s_addc_u32 s29, s3, s25
	s_and_b64 s[38:39], s[6:7], exec
	s_cselect_b32 s55, s29, s37
	s_cselect_b32 s56, s28, s36
	s_add_u32 s34, s34, 0x40080
	s_addc_u32 s35, s35, 0
	s_add_u32 s57, s36, 0x100
	v_mov_b32_e32 v0, 0
	s_addc_u32 s58, s37, 0
	s_mov_b32 s59, -2
	s_waitcnt lgkmcnt(0)
	v_mov_b32_e32 v1, v0
	v_mov_b32_e32 v2, v0
	v_mov_b32_e32 v3, v0
	v_mov_b32_e32 v4, v0
	v_mov_b32_e32 v5, v0
	v_mov_b32_e32 v6, v0
	v_mov_b32_e32 v7, v0
	v_mov_b32_e32 v16, v0
	v_mov_b32_e32 v17, v0
	v_mov_b32_e32 v18, v0
	v_mov_b32_e32 v19, v0
	v_mov_b32_e32 v20, v0
	v_mov_b32_e32 v21, v0
	v_mov_b32_e32 v22, v0
	v_mov_b32_e32 v23, v0
	v_mov_b32_e32 v32, v0
	v_mov_b32_e32 v33, v0
	v_mov_b32_e32 v34, v0
	v_mov_b32_e32 v35, v0
	v_mov_b32_e32 v36, v0
	v_mov_b32_e32 v37, v0
	v_mov_b32_e32 v38, v0
	v_mov_b32_e32 v39, v0
	v_mov_b32_e32 v48, v0
	v_mov_b32_e32 v49, v0
	v_mov_b32_e32 v50, v0
	v_mov_b32_e32 v51, v0
	v_mov_b32_e32 v52, v0
	v_mov_b32_e32 v53, v0
	v_mov_b32_e32 v54, v0
	v_mov_b32_e32 v55, v0
	v_mov_b32_e32 v8, v0
	v_mov_b32_e32 v9, v0
	v_mov_b32_e32 v10, v0
	v_mov_b32_e32 v11, v0
	v_mov_b32_e32 v12, v0
	v_mov_b32_e32 v13, v0
	v_mov_b32_e32 v14, v0
	v_mov_b32_e32 v15, v0
	v_mov_b32_e32 v24, v0
	v_mov_b32_e32 v25, v0
	v_mov_b32_e32 v26, v0
	v_mov_b32_e32 v27, v0
	v_mov_b32_e32 v28, v0
	v_mov_b32_e32 v29, v0
	v_mov_b32_e32 v30, v0
	v_mov_b32_e32 v31, v0
	v_mov_b32_e32 v40, v0
	v_mov_b32_e32 v41, v0
	v_mov_b32_e32 v42, v0
	v_mov_b32_e32 v43, v0
	v_mov_b32_e32 v44, v0
	v_mov_b32_e32 v45, v0
	v_mov_b32_e32 v46, v0
	v_mov_b32_e32 v47, v0
	v_mov_b32_e32 v56, v0
	v_mov_b32_e32 v57, v0
	v_mov_b32_e32 v58, v0
	v_mov_b32_e32 v59, v0
	v_mov_b32_e32 v60, v0
	v_mov_b32_e32 v61, v0
	v_mov_b32_e32 v62, v0
	v_mov_b32_e32 v63, v0
	v_mov_b32_e32 v64, v0
	v_mov_b32_e32 v65, v0
	v_mov_b32_e32 v66, v0
	v_mov_b32_e32 v67, v0
	v_mov_b32_e32 v68, v0
	v_mov_b32_e32 v69, v0
	v_mov_b32_e32 v70, v0
	v_mov_b32_e32 v71, v0
	v_mov_b32_e32 v80, v0
	v_mov_b32_e32 v81, v0
	v_mov_b32_e32 v82, v0
	v_mov_b32_e32 v83, v0
	v_mov_b32_e32 v84, v0
	v_mov_b32_e32 v85, v0
	v_mov_b32_e32 v86, v0
	v_mov_b32_e32 v87, v0
	v_mov_b32_e32 v96, v0
	v_mov_b32_e32 v97, v0
	v_mov_b32_e32 v98, v0
	v_mov_b32_e32 v99, v0
	v_mov_b32_e32 v100, v0
	v_mov_b32_e32 v101, v0
	v_mov_b32_e32 v102, v0
	v_mov_b32_e32 v103, v0
	v_mov_b32_e32 v112, v0
	v_mov_b32_e32 v113, v0
	v_mov_b32_e32 v114, v0
	v_mov_b32_e32 v115, v0
	v_mov_b32_e32 v116, v0
	v_mov_b32_e32 v117, v0
	v_mov_b32_e32 v118, v0
	v_mov_b32_e32 v119, v0
	v_mov_b32_e32 v72, v0
	v_mov_b32_e32 v73, v0
	v_mov_b32_e32 v74, v0
	v_mov_b32_e32 v75, v0
	v_mov_b32_e32 v76, v0
	v_mov_b32_e32 v77, v0
	v_mov_b32_e32 v78, v0
	v_mov_b32_e32 v79, v0
	v_mov_b32_e32 v88, v0
	v_mov_b32_e32 v89, v0
	v_mov_b32_e32 v90, v0
	v_mov_b32_e32 v91, v0
	v_mov_b32_e32 v92, v0
	v_mov_b32_e32 v93, v0
	v_mov_b32_e32 v94, v0
	v_mov_b32_e32 v95, v0
	v_mov_b32_e32 v104, v0
	v_mov_b32_e32 v105, v0
	v_mov_b32_e32 v106, v0
	v_mov_b32_e32 v107, v0
	v_mov_b32_e32 v108, v0
	v_mov_b32_e32 v109, v0
	v_mov_b32_e32 v110, v0
	v_mov_b32_e32 v111, v0
	v_mov_b32_e32 v120, v0
	v_mov_b32_e32 v121, v0
	v_mov_b32_e32 v122, v0
	v_mov_b32_e32 v123, v0
	v_mov_b32_e32 v124, v0
	v_mov_b32_e32 v125, v0
	v_mov_b32_e32 v126, v0
	v_mov_b32_e32 v127, v0
	.p2align 6

; #define PG8_LDA(dst, b, h) do { _Pragma("unroll") for (int m = 0; m < 4; ++m) _Pragma("unroll") for (int k = 0; k < 2; ++k) dst[m][k] = *(const LAS bf16x8*)(lds + PG8_SA(b, h) + aoff + m * 2048 + k * 1024); } while (0)
; template <class Epi>
; __device__ __forceinline__ void gemm_phase(LAS unsigned char* lds, const Gemm g, const Order& S, const Epi& E) {
;     ...
;         const bool has_next = S.next(ui + 1, nxt);
;         const char* nA = has_next ? (const char*)g.A + nxt.aoff : cA; const char* nB = has_next ? (const char*)g.Bt + nxt.boff : cB;
;         for (int t = 0; t < nt; t += 2) {
;             const bool last = (t == nt - 2);
;             const char* a1 = cA + (size_t)(t + 1) * kstep;
;             const char* a2 = last ? nA : cA + (size_t)(t + 2) * kstep; const char* b2 = last ? nB : cB + (size_t)(t + 2) * kstep;
;             const char* a3 = a2 + kstep; const char* b3 = b2 + kstep;
;             PG8_LDB(B0, 0, 0); PG8_LDB(B1, 0, 1); PG8_SCHED; PG8_LDA(At, 0, 0); PG8_STAGE(PG8_SA(1, 1), a1 + hstepA, voffA);
;             PG8_WAIT_V(8); PG8_WAIT_L(0); PG8_BAR; PG8_MMA(0, 0, At, B0); PG8_MMA(0, 1, At, B1); PG8_BAR; PG8_SCHED;
;             PG8_LDA(At, 0, 1); PG8_STAGE(PG8_SB(0, 0), b2, voffB); PG8_STAGE(PG8_SB(0, 1), b2 + hstepB, voffB); PG8_STAGE(PG8_SA(0, 0), a2, voffA);
;             PG8_WAIT_V(8); PG8_WAIT_L(0); PG8_BAR; PG8_MMA(1, 0, At, B0); PG8_MMA(1, 1, At, B1); PG8_BAR; PG8_SCHED;
;             PG8_LDB(B0, 1, 0); PG8_LDB(B1, 1, 1); PG8_SCHED; PG8_LDA(At, 1, 0); PG8_STAGE(PG8_SA(0, 1), a2 + hstepA, voffA);
;             PG8_WAIT_V(8); PG8_WAIT_L(0); PG8_BAR; PG8_MMA(0, 0, At, B0); PG8_MMA(0, 1, At, B1); PG8_BAR; PG8_SCHED;
;             PG8_LDA(At, 1, 1); PG8_STAGE(PG8_SB(1, 0), b3, voffB); PG8_STAGE(PG8_SB(1, 1), b3 + hstepB, voffB); PG8_STAGE(PG8_SA(1, 0), a3, voffA);
;             PG8_WAIT_V(8); PG8_WAIT_L(0); PG8_BAR; PG8_MMA(1, 0, At, B0); PG8_MMA(1, 1, At, B1); PG8_BAR; PG8_SCHED;
;         }
;         if (wr == 0) PG8_BAR;
;         E(acc, cur, wr, wc, fr, fq);
;         if (!has_next) break;
; #pragma unroll
;         for (int a = 0; a < 2; ++a)
; #pragma unroll
;             for (int b = 0; b < 2; ++b)
; #pragma unroll
;                 for (int m = 0; m < 4; ++m)
; #pragma unroll
;                     for (int n = 0; n < 2; ++n) acc[a][b][m][n] = (f32x4){0.f, 0.f, 0.f, 0.f};
;         cur = nxt; cA = nA; cB = nB; ++ui;
.LBB0_860:
	s_add_u32 s54, s44, s50
	s_addc_u32 s55, s45, s51
	s_and_b64 s[18:19], s[12:13], exec
	s_cselect_b32 s47, s55, s15
	s_cselect_b32 s49, s54, s14
	s_add_u32 s56, s2, s52
	s_addc_u32 s57, s3, s53
	s_and_b64 s[18:19], s[12:13], exec
	s_cselect_b32 s84, s57, s17
	s_cselect_b32 s85, s56, s16
	s_add_u32 s14, s14, 0x80080
	s_addc_u32 s15, s15, 0
	s_add_u32 s88, s16, 0x100
	v_mov_b32_e32 v20, 0
	s_addc_u32 s89, s17, 0
	s_mov_b32 s90, -2
	v_mov_b32_e32 v21, v20
	v_mov_b32_e32 v22, v20
	v_mov_b32_e32 v23, v20
	v_mov_b32_e32 v44, v20
	v_mov_b32_e32 v45, v20
	v_mov_b32_e32 v46, v20
	v_mov_b32_e32 v47, v20
	v_mov_b32_e32 v28, v20
	v_mov_b32_e32 v29, v20
	v_mov_b32_e32 v30, v20
	v_mov_b32_e32 v31, v20
	v_mov_b32_e32 v48, v20
	v_mov_b32_e32 v49, v20
	v_mov_b32_e32 v50, v20
	v_mov_b32_e32 v51, v20
	v_mov_b32_e32 v32, v20
	v_mov_b32_e32 v33, v20
	v_mov_b32_e32 v34, v20
	v_mov_b32_e32 v35, v20
	v_mov_b32_e32 v52, v20
	v_mov_b32_e32 v53, v20
	v_mov_b32_e32 v54, v20
	v_mov_b32_e32 v55, v20
	v_mov_b32_e32 v8, v20
	v_mov_b32_e32 v9, v20
	v_mov_b32_e32 v10, v20
	v_mov_b32_e32 v11, v20
	v_mov_b32_e32 v12, v20
	v_mov_b32_e32 v13, v20
	v_mov_b32_e32 v14, v20
	v_mov_b32_e32 v15, v20
	v_mov_b32_e32 v0, v20
	v_mov_b32_e32 v1, v20
	v_mov_b32_e32 v2, v20
	v_mov_b32_e32 v3, v20
	v_mov_b32_e32 v4, v20
	v_mov_b32_e32 v5, v20
	v_mov_b32_e32 v6, v20
	v_mov_b32_e32 v7, v20
	v_mov_b32_e32 v36, v20
	v_mov_b32_e32 v37, v20
	v_mov_b32_e32 v38, v20
	v_mov_b32_e32 v39, v20
	v_mov_b32_e32 v56, v20
	v_mov_b32_e32 v57, v20
	v_mov_b32_e32 v58, v20
	v_mov_b32_e32 v59, v20
	v_mov_b32_e32 v40, v20
	v_mov_b32_e32 v41, v20
	v_mov_b32_e32 v42, v20
	v_mov_b32_e32 v43, v20
	v_mov_b32_e32 v60, v20
	v_mov_b32_e32 v61, v20
	v_mov_b32_e32 v62, v20
	v_mov_b32_e32 v63, v20
	v_mov_b32_e32 v16, v20
	v_mov_b32_e32 v17, v20
	v_mov_b32_e32 v18, v20
	v_mov_b32_e32 v19, v20
	v_mov_b32_e32 v24, v20
	v_mov_b32_e32 v25, v20
	v_mov_b32_e32 v26, v20
	v_mov_b32_e32 v27, v20
	v_mov_b32_e32 v88, v20
	v_mov_b32_e32 v89, v20
	v_mov_b32_e32 v90, v20
	v_mov_b32_e32 v91, v20
	v_mov_b32_e32 v108, v20
	v_mov_b32_e32 v109, v20
	v_mov_b32_e32 v110, v20
	v_mov_b32_e32 v111, v20
	v_mov_b32_e32 v92, v20
	v_mov_b32_e32 v93, v20
	v_mov_b32_e32 v94, v20
	v_mov_b32_e32 v95, v20
	v_mov_b32_e32 v112, v20
	v_mov_b32_e32 v113, v20
	v_mov_b32_e32 v114, v20
	v_mov_b32_e32 v115, v20
	v_mov_b32_e32 v96, v20
	v_mov_b32_e32 v97, v20
	v_mov_b32_e32 v98, v20
	v_mov_b32_e32 v99, v20
	v_mov_b32_e32 v116, v20
	v_mov_b32_e32 v117, v20
	v_mov_b32_e32 v118, v20
	v_mov_b32_e32 v119, v20
	v_mov_b32_e32 v72, v20
	v_mov_b32_e32 v73, v20
	v_mov_b32_e32 v74, v20
	v_mov_b32_e32 v75, v20
	v_mov_b32_e32 v76, v20
	v_mov_b32_e32 v77, v20
	v_mov_b32_e32 v78, v20
	v_mov_b32_e32 v79, v20
	v_mov_b32_e32 v64, v20
	v_mov_b32_e32 v65, v20
	v_mov_b32_e32 v66, v20
	v_mov_b32_e32 v67, v20
	v_mov_b32_e32 v68, v20
	v_mov_b32_e32 v69, v20
	v_mov_b32_e32 v70, v20
	v_mov_b32_e32 v71, v20
	v_mov_b32_e32 v100, v20
	v_mov_b32_e32 v101, v20
	v_mov_b32_e32 v102, v20
	v_mov_b32_e32 v103, v20
	v_mov_b32_e32 v120, v20
	v_mov_b32_e32 v121, v20
	v_mov_b32_e32 v122, v20
	v_mov_b32_e32 v123, v20
	v_mov_b32_e32 v104, v20
	v_mov_b32_e32 v105, v20
	v_mov_b32_e32 v106, v20
	v_mov_b32_e32 v107, v20
	v_mov_b32_e32 v124, v20
	v_mov_b32_e32 v125, v20
	v_mov_b32_e32 v126, v20
	v_mov_b32_e32 v127, v20
	v_mov_b32_e32 v80, v20
	v_mov_b32_e32 v81, v20
	v_mov_b32_e32 v82, v20
	v_mov_b32_e32 v83, v20
	v_mov_b32_e32 v84, v20
	v_mov_b32_e32 v85, v20
	v_mov_b32_e32 v86, v20
	v_mov_b32_e32 v87, v20
	.p2align 6

; #define PG8_LDA(dst, b, h) do { _Pragma("unroll") for (int m = 0; m < 4; ++m) _Pragma("unroll") for (int k = 0; k < 2; ++k) dst[m][k] = *(const LAS bf16x8*)(lds + PG8_SA(b, h) + aoff + m * 2048 + k * 1024); } while (0)
; template <class Epi>
; __device__ __forceinline__ void gemm_phase(LAS unsigned char* lds, const Gemm g, const Order& S, const Epi& E) {
;     ...
;         const bool has_next = S.next(ui + 1, nxt);
;         const char* nA = has_next ? (const char*)g.A + nxt.aoff : cA; const char* nB = has_next ? (const char*)g.Bt + nxt.boff : cB;
;         for (int t = 0; t < nt; t += 2) {
;             const bool last = (t == nt - 2);
;             const char* a1 = cA + (size_t)(t + 1) * kstep;
;             const char* a2 = last ? nA : cA + (size_t)(t + 2) * kstep; const char* b2 = last ? nB : cB + (size_t)(t + 2) * kstep;
;             const char* a3 = a2 + kstep; const char* b3 = b2 + kstep;
;             PG8_LDB(B0, 0, 0); PG8_LDB(B1, 0, 1); PG8_SCHED; PG8_LDA(At, 0, 0); PG8_STAGE(PG8_SA(1, 1), a1 + hstepA, voffA);
;             PG8_WAIT_V(8); PG8_WAIT_L(0); PG8_BAR; PG8_MMA(0, 0, At, B0); PG8_MMA(0, 1, At, B1); PG8_BAR; PG8_SCHED;
;             PG8_LDA(At, 0, 1); PG8_STAGE(PG8_SB(0, 0), b2, voffB); PG8_STAGE(PG8_SB(0, 1), b2 + hstepB, voffB); PG8_STAGE(PG8_SA(0, 0), a2, voffA);
;             PG8_WAIT_V(8); PG8_WAIT_L(0); PG8_BAR; PG8_MMA(1, 0, At, B0); PG8_MMA(1, 1, At, B1); PG8_BAR; PG8_SCHED;
;             PG8_LDB(B0, 1, 0); PG8_LDB(B1, 1, 1); PG8_SCHED; PG8_LDA(At, 1, 0); PG8_STAGE(PG8_SA(0, 1), a2 + hstepA, voffA);
;             PG8_WAIT_V(8); PG8_WAIT_L(0); PG8_BAR; PG8_MMA(0, 0, At, B0); PG8_MMA(0, 1, At, B1); PG8_BAR; PG8_SCHED;
;             PG8_LDA(At, 1, 1); PG8_STAGE(PG8_SB(1, 0), b3, voffB); PG8_STAGE(PG8_SB(1, 1), b3 + hstepB, voffB); PG8_STAGE(PG8_SA(1, 0), a3, voffA);
;             PG8_WAIT_V(8); PG8_WAIT_L(0); PG8_BAR; PG8_MMA(1, 0, At, B0); PG8_MMA(1, 1, At, B1); PG8_BAR; PG8_SCHED;
;         }
;         if (wr == 0) PG8_BAR;
;         E(acc, cur, wr, wc, fr, fq);
;         if (!has_next) break;
; #pragma unroll
;         for (int a = 0; a < 2; ++a)
; #pragma unroll
;             for (int b = 0; b < 2; ++b)
; #pragma unroll
;                 for (int m = 0; m < 4; ++m)
; #pragma unroll
;                     for (int n = 0; n < 2; ++n) acc[a][b][m][n] = (f32x4){0.f, 0.f, 0.f, 0.f};
;         cur = nxt; cA = nA; cB = nB; ++ui;
.LBB0_1022:
	s_add_u32 s26, s3, s22
	s_addc_u32 s27, s33, s23
	s_and_b64 s[28:29], s[4:5], exec
	s_cselect_b32 s57, s27, s31
	s_cselect_b32 s58, s26, s30
	s_add_u32 s28, s38, s24
	s_addc_u32 s29, s39, s25
	s_and_b64 s[36:37], s[4:5], exec
	s_cselect_b32 s59, s29, s35
	s_cselect_b32 s60, s28, s34
	s_add_u32 s30, s30, 0x160080
	s_addc_u32 s31, s31, 0
	s_add_u32 s61, s34, 0x100
	v_mov_b32_e32 v0, 0
	s_addc_u32 s62, s35, 0
	s_mov_b32 s63, -2
	v_mov_b32_e32 v1, v0
	v_mov_b32_e32 v2, v0
	v_mov_b32_e32 v3, v0
	v_mov_b32_e32 v4, v0
	v_mov_b32_e32 v5, v0
	v_mov_b32_e32 v6, v0
	v_mov_b32_e32 v7, v0
	v_mov_b32_e32 v12, v0
	v_mov_b32_e32 v13, v0
	v_mov_b32_e32 v14, v0
	v_mov_b32_e32 v15, v0
	v_mov_b32_e32 v20, v0
	v_mov_b32_e32 v21, v0
	v_mov_b32_e32 v22, v0
	v_mov_b32_e32 v23, v0
	v_mov_b32_e32 v28, v0
	v_mov_b32_e32 v29, v0
	v_mov_b32_e32 v30, v0
	v_mov_b32_e32 v31, v0
	v_mov_b32_e32 v36, v0
	v_mov_b32_e32 v37, v0
	v_mov_b32_e32 v38, v0
	v_mov_b32_e32 v39, v0
	v_mov_b32_e32 v44, v0
	v_mov_b32_e32 v45, v0
	v_mov_b32_e32 v46, v0
	v_mov_b32_e32 v47, v0
	v_mov_b32_e32 v52, v0
	v_mov_b32_e32 v53, v0
	v_mov_b32_e32 v54, v0
	v_mov_b32_e32 v55, v0
	v_mov_b32_e32 v8, v0
	v_mov_b32_e32 v9, v0
	v_mov_b32_e32 v10, v0
	v_mov_b32_e32 v11, v0
	v_mov_b32_e32 v16, v0
	v_mov_b32_e32 v17, v0
	v_mov_b32_e32 v18, v0
	v_mov_b32_e32 v19, v0
	v_mov_b32_e32 v24, v0
	v_mov_b32_e32 v25, v0
	v_mov_b32_e32 v26, v0
	v_mov_b32_e32 v27, v0
	v_mov_b32_e32 v32, v0
	v_mov_b32_e32 v33, v0
	v_mov_b32_e32 v34, v0
	v_mov_b32_e32 v35, v0
	v_mov_b32_e32 v40, v0
	v_mov_b32_e32 v41, v0
	v_mov_b32_e32 v42, v0
	v_mov_b32_e32 v43, v0
	v_mov_b32_e32 v48, v0
	v_mov_b32_e32 v49, v0
	v_mov_b32_e32 v50, v0
	v_mov_b32_e32 v51, v0
	v_mov_b32_e32 v56, v0
	v_mov_b32_e32 v57, v0
	v_mov_b32_e32 v58, v0
	v_mov_b32_e32 v59, v0
	v_mov_b32_e32 v60, v0
	v_mov_b32_e32 v61, v0
	v_mov_b32_e32 v62, v0
	v_mov_b32_e32 v63, v0
	v_mov_b32_e32 v64, v0
	v_mov_b32_e32 v65, v0
	v_mov_b32_e32 v66, v0
	v_mov_b32_e32 v67, v0
	v_mov_b32_e32 v68, v0
	v_mov_b32_e32 v69, v0
	v_mov_b32_e32 v70, v0
	v_mov_b32_e32 v71, v0
	v_mov_b32_e32 v76, v0
	v_mov_b32_e32 v77, v0
	v_mov_b32_e32 v78, v0
	v_mov_b32_e32 v79, v0
	v_mov_b32_e32 v84, v0
	v_mov_b32_e32 v85, v0
	v_mov_b32_e32 v86, v0
	v_mov_b32_e32 v87, v0
	v_mov_b32_e32 v92, v0
	v_mov_b32_e32 v93, v0
	v_mov_b32_e32 v94, v0
	v_mov_b32_e32 v95, v0
	v_mov_b32_e32 v100, v0
	v_mov_b32_e32 v101, v0
	v_mov_b32_e32 v102, v0
	v_mov_b32_e32 v103, v0
	v_mov_b32_e32 v108, v0
	v_mov_b32_e32 v109, v0
	v_mov_b32_e32 v110, v0
	v_mov_b32_e32 v111, v0
	v_mov_b32_e32 v116, v0
	v_mov_b32_e32 v117, v0
	v_mov_b32_e32 v118, v0
	v_mov_b32_e32 v119, v0
	v_mov_b32_e32 v72, v0
	v_mov_b32_e32 v73, v0
	v_mov_b32_e32 v74, v0
	v_mov_b32_e32 v75, v0
	v_mov_b32_e32 v80, v0
	v_mov_b32_e32 v81, v0
	v_mov_b32_e32 v82, v0
	v_mov_b32_e32 v83, v0
	v_mov_b32_e32 v88, v0
	v_mov_b32_e32 v89, v0
	v_mov_b32_e32 v90, v0
	v_mov_b32_e32 v91, v0
	v_mov_b32_e32 v96, v0
	v_mov_b32_e32 v97, v0
	v_mov_b32_e32 v98, v0
	v_mov_b32_e32 v99, v0
	v_mov_b32_e32 v104, v0
	v_mov_b32_e32 v105, v0
	v_mov_b32_e32 v106, v0
	v_mov_b32_e32 v107, v0
	v_mov_b32_e32 v112, v0
	v_mov_b32_e32 v113, v0
	v_mov_b32_e32 v114, v0
	v_mov_b32_e32 v115, v0
	v_mov_b32_e32 v120, v0
	v_mov_b32_e32 v121, v0
	v_mov_b32_e32 v122, v0
	v_mov_b32_e32 v123, v0
	v_mov_b32_e32 v124, v0
	v_mov_b32_e32 v125, v0
	v_mov_b32_e32 v126, v0
	v_mov_b32_e32 v127, v0
	.p2align 6
